# v3 + P7 conv halo fix-up rewritten straight-line (all loads in flight at once, float4 per thread)
# baseline (speedup 1.0000x reference)
; __device__ __forceinline__ unsigned f2bf(float f) { unsigned u = __builtin_bit_cast(unsigned, f); return (u + 0x7fffu + ((u >> 16) & 1u)) >> 16; }
; __device__ __forceinline__ float sigm_f(float x) { return __builtin_amdgcn_rcpf(1.0f + __builtin_amdgcn_exp2f(-x * LOG2E_F)); }
; __device__ __forceinline__ void conv_fixup(int pm, const float* cwp, const float* cbp, unsigned char* ws, int tid) {
;     const float* HA = (const float*)(ws + WS_HALOA); const float* HU = (const float*)(ws + WS_HALOU); const float* LA = (const float*)(ws + WS_LASTA); bf16* G = (bf16*)(ws + WS_G);
;     const bool first = (pm & 31) == 0;
;     for (int e = tid; e < 2 * DFF; e += NWAVES * 64) {
;         const int i = e >= DFF, c = e - i * DFF;
;         const float a = HA[(size_t)(pm * 2 + i) * DFF + c], u = HU[(size_t)(pm * 2 + i) * DFF + c];
;         float p1, p2;
;         if (i == 0) { p1 = first ? 0.f : LA[(size_t)((pm - 1) * 2 + 1) * DFF + c]; p2 = first ? 0.f : LA[(size_t)((pm - 1) * 2) * DFF + c]; }
;         else { p1 = HA[(size_t)(pm * 2) * DFF + c]; p2 = first ? 0.f : LA[(size_t)((pm - 1) * 2 + 1) * DFF + c]; }
;         const float cc = cbp[c] + cwp[c] * p2 + cwp[DFF + c] * p1 + cwp[2 * DFF + c] * a;
;         G[(size_t)(pm * 256 + i) * DFF + c] = (bf16)f2bf(cc * sigm_f(cc) * u);
;     }
; }
; __global__ void __launch_bounds__(NWAVES * 64, 2) fwd(Args args_unused) {
;     ...
;       { const float* cwp = A->in.cw; const float* cbp = A->in.cb; pg8::Unit u; for (int rep_ = 0; rep_ < REP_FIX; ++rep_) if (S.S0.next(0, u)) conv_fixup(u.pm, cwp, cbp, ws, tid); }
.LBB0_1151:
.LBB0_1152:
	s_add_u32 s18, s10, 0x2100000
	s_addc_u32 s19, s11, 0
	s_add_u32 s20, s10, 0x2300000
	s_addc_u32 s21, s11, 0
	s_add_u32 s22, s10, 0x2500000
	s_addc_u32 s23, s11, 0
	s_ashr_i32 s0, s58, 31
	s_lshr_b32 s0, s0, 29
	s_add_i32 s0, s58, s0
	s_ashr_i32 s42, s0, 3
	s_and_b32 s0, s0, -8
	s_sub_i32 s47, s58, s0
	s_lshl_b32 s43, s47, 5
	s_mul_i32 s46, s47, 33
	s_cmp_lt_i32 s47, 0
	s_cselect_b32 s0, s46, s43
	s_add_i32 s0, s0, s42
	s_ashr_i32 s1, s0, 31
	s_lshr_b32 s1, s1, 27
	s_add_i32 s1, s0, s1
	s_ashr_i32 s2, s1, 5
	s_lshl_b32 s2, s2, 3
	s_sub_i32 s3, 64, s2
	s_min_u32 s3, s3, 8
	s_andn2_b32 s1, s1, 31
	s_sub_i32 s24, s0, s1
	v_cvt_f32_ubyte0_e32 v2, s3
	v_cvt_f32_i32_e32 v1, s24
	v_rcp_iflag_f32_e32 v3, v2
	s_ashr_i32 s0, s24, 30
	s_load_dwordx4 s[12:15], s[4:5], 0x98
	s_or_b32 s4, s0, 1
	v_mul_f32_e32 v3, v1, v3
	v_trunc_f32_e32 v3, v3
	v_fma_f32 v1, -v3, v2, v1
	v_cvt_i32_f32_e32 v3, v3
	v_cmp_ge_f32_e64 s[0:1], |v1|, v2
	s_and_b64 s[0:1], s[0:1], exec
	s_cselect_b32 s0, s4, 0
	v_readfirstlane_b32 s1, v3
	s_add_i32 s0, s1, s0
	s_mul_i32 s0, s0, s3
	s_sub_i32 s0, s24, s0
	s_sext_i32_i8 s0, s0
	s_add_i32 s2, s2, s0
	s_and_b32 s0, s2, 31
	s_cmp_lg_u32 s0, 0
	s_cselect_b64 s[24:25], -1, 0
	s_lshl_b32 s0, s2, 1
	s_lshl_b32 s1, s2, 8
	s_mulk_i32 s2, 0x5800
	s_add_i32 s3, s0, -1
	s_add_i32 s26, s2, 0xffffd400
	s_mul_hi_i32 s27, s3, 0x2c00
	s_add_u32 s28, s22, s26
	s_addc_u32 s29, s23, s27
	s_add_i32 s3, s0, -2
	s_add_i32 s30, s2, 0xffffa800
	s_mul_hi_i32 s31, s3, 0x2c00
	s_mul_hi_i32 s3, s0, 0x2c00
	s_add_u32 s34, s18, s2
	v_cndmask_b32_e64 v2, 0, 1, s[24:25]
	s_addc_u32 s35, s19, s3
	s_add_u32 s36, s20, s2
	s_addc_u32 s37, s21, s3
	s_add_u32 s38, s22, s30
	s_addc_u32 s39, s23, s31
	s_mul_i32 s48, s1, 0x1600
	s_add_u32 s48, s6, s48
	s_addc_u32 s49, s7, 0
	s_add_u32 s22, s48, 0x1600
	s_addc_u32 s23, s49, 0
	s_add_u32 s26, s34, 0x2c00
	s_addc_u32 s27, s35, 0
	s_add_u32 s30, s36, 0x2c00
	s_addc_u32 s31, s37, 0
	v_mov_b64_e32 v[4:5], s[6:7]
	v_lshlrev_b32_e32 v1, 4, v0
	v_lshrrev_b32_e32 v3, 6, v0
	s_waitcnt lgkmcnt(0)
	s_add_u32 s40, s12, 0x2c00
	s_addc_u32 s41, s13, 0
	s_add_u32 s44, s12, 0x5800
	s_addc_u32 s45, s13, 0
	v_readfirstlane_b32 s4, v3
	global_load_dwordx4 v[16:19], v1, s[34:35]
	global_load_dwordx4 v[20:23], v1, s[36:37]
	global_load_dwordx4 v[24:27], v1, s[28:29]
	global_load_dwordx4 v[28:31], v1, s[38:39]
	global_load_dwordx4 v[32:35], v1, s[26:27]
	global_load_dwordx4 v[36:39], v1, s[30:31]
	global_load_dwordx4 v[40:43], v1, s[34:35]
	global_load_dwordx4 v[44:47], v1, s[28:29]
	global_load_dwordx4 v[48:51], v1, s[12:13]
	global_load_dwordx4 v[52:55], v1, s[40:41]
	global_load_dwordx4 v[56:59], v1, s[44:45]
	global_load_dwordx4 v[60:63], v1, s[14:15]
	s_cmp_ge_u32 s4, 3
	s_movk_i32 s5, 0x2000
	s_cselect_b32 s5, 0x1400, s5
	s_cselect_b32 s0, s26, s34
	s_cselect_b32 s1, s27, s35
	s_cselect_b32 s2, s30, s36
	s_cselect_b32 s3, s31, s37
	s_cselect_b32 s32, s34, s28
	s_cselect_b32 s33, s35, s29
	s_cselect_b32 s98, s28, s38
	s_cselect_b32 s99, s29, s39
	s_cselect_b64 s[100:101], -1, s[24:25]
	v_add_u32_e32 v2, s5, v1
	s_cmp_lt_u32 s4, 6
	s_cbranch_scc0 .Lfix_skip3a
	global_load_dwordx4 v[64:67], v2, s[0:1]
	global_load_dwordx4 v[68:71], v2, s[2:3]
	global_load_dwordx4 v[72:75], v2, s[32:33]
	global_load_dwordx4 v[76:79], v2, s[98:99]
	global_load_dwordx4 v[80:83], v2, s[12:13]
	global_load_dwordx4 v[84:87], v2, s[40:41]
	global_load_dwordx4 v[88:91], v2, s[44:45]
	global_load_dwordx4 v[92:95], v2, s[14:15]
; __device__ __forceinline__ unsigned f2bf(float f) { unsigned u = __builtin_bit_cast(unsigned, f); return (u + 0x7fffu + ((u >> 16) & 1u)) >> 16; }
; __device__ __forceinline__ float sigm_f(float x) { return __builtin_amdgcn_rcpf(1.0f + __builtin_amdgcn_exp2f(-x * LOG2E_F)); }
; __device__ __forceinline__ void conv_fixup(int pm, const float* cwp, const float* cbp, unsigned char* ws, int tid) {
;     const float* HA = (const float*)(ws + WS_HALOA); const float* HU = (const float*)(ws + WS_HALOU); const float* LA = (const float*)(ws + WS_LASTA); bf16* G = (bf16*)(ws + WS_G);
;     const bool first = (pm & 31) == 0;
;     for (int e = tid; e < 2 * DFF; e += NWAVES * 64) {
;         const int i = e >= DFF, c = e - i * DFF;
;         const float a = HA[(size_t)(pm * 2 + i) * DFF + c], u = HU[(size_t)(pm * 2 + i) * DFF + c];
;         float p1, p2;
;         if (i == 0) { p1 = first ? 0.f : LA[(size_t)((pm - 1) * 2 + 1) * DFF + c]; p2 = first ? 0.f : LA[(size_t)((pm - 1) * 2) * DFF + c]; }
;         else { p1 = HA[(size_t)(pm * 2) * DFF + c]; p2 = first ? 0.f : LA[(size_t)((pm - 1) * 2 + 1) * DFF + c]; }
;         const float cc = cbp[c] + cwp[c] * p2 + cwp[DFF + c] * p1 + cwp[2 * DFF + c] * a;
;         G[(size_t)(pm * 256 + i) * DFF + c] = (bf16)f2bf(cc * sigm_f(cc) * u);
;     }
; }
.Lfix_skip3a:
	s_waitcnt vmcnt(0)
	v_lshlrev_b32_e32 v3, 3, v0
	v_cndmask_b32_e64 v24, 0, v24, s[24:25]
	v_cndmask_b32_e64 v25, 0, v25, s[24:25]
	v_cndmask_b32_e64 v26, 0, v26, s[24:25]
	v_cndmask_b32_e64 v27, 0, v27, s[24:25]
	v_cndmask_b32_e64 v28, 0, v28, s[24:25]
	v_cndmask_b32_e64 v29, 0, v29, s[24:25]
	v_cndmask_b32_e64 v30, 0, v30, s[24:25]
	v_cndmask_b32_e64 v31, 0, v31, s[24:25]
	v_fma_f32 v96, v28, v48, v60
	v_fma_f32 v97, v29, v49, v61
	v_fma_f32 v98, v30, v50, v62
	v_fma_f32 v99, v31, v51, v63
	v_mul_f32_e32 v104, v24, v52
	v_mul_f32_e32 v105, v25, v53
	v_mul_f32_e32 v106, v26, v54
	v_mul_f32_e32 v107, v27, v55
	v_add_f32_e32 v96, v96, v104
	v_add_f32_e32 v97, v97, v105
	v_add_f32_e32 v98, v98, v106
	v_add_f32_e32 v99, v99, v107
	v_mul_f32_e32 v104, v16, v56
	v_mul_f32_e32 v105, v17, v57
	v_mul_f32_e32 v106, v18, v58
	v_mul_f32_e32 v107, v19, v59
	v_add_f32_e32 v96, v96, v104
	v_add_f32_e32 v97, v97, v105
	v_add_f32_e32 v98, v98, v106
	v_add_f32_e32 v99, v99, v107
	v_mul_f32_e32 v100, 0xbfb8aa3b, v96
	v_mul_f32_e32 v101, 0xbfb8aa3b, v97
	v_mul_f32_e32 v102, 0xbfb8aa3b, v98
	v_mul_f32_e32 v103, 0xbfb8aa3b, v99
	v_exp_f32_e32 v100, v100
	v_exp_f32_e32 v101, v101
	v_exp_f32_e32 v102, v102
	v_exp_f32_e32 v103, v103
	v_add_f32_e32 v100, 1.0, v100
	v_add_f32_e32 v101, 1.0, v101
	v_add_f32_e32 v102, 1.0, v102
	v_add_f32_e32 v103, 1.0, v103
	v_rcp_f32_e32 v100, v100
	v_rcp_f32_e32 v101, v101
	v_rcp_f32_e32 v102, v102
	v_rcp_f32_e32 v103, v103
	v_mul_f32_e32 v96, v96, v100
	v_mul_f32_e32 v97, v97, v101
	v_mul_f32_e32 v98, v98, v102
	v_mul_f32_e32 v99, v99, v103
	v_mul_f32_e32 v96, v20, v96
	v_mul_f32_e32 v97, v21, v97
	v_mul_f32_e32 v98, v22, v98
	v_mul_f32_e32 v99, v23, v99
	v_cvt_pk_bf16_f32 v104, v96, v97
	v_cvt_pk_bf16_f32 v105, v98, v99
	global_store_dwordx2 v3, v[104:105], s[48:49]
	v_cndmask_b32_e64 v44, 0, v44, s[24:25]
	v_cndmask_b32_e64 v45, 0, v45, s[24:25]
	v_cndmask_b32_e64 v46, 0, v46, s[24:25]
	v_cndmask_b32_e64 v47, 0, v47, s[24:25]
	v_fma_f32 v108, v44, v48, v60
	v_fma_f32 v109, v45, v49, v61
	v_fma_f32 v110, v46, v50, v62
	v_fma_f32 v111, v47, v51, v63
	v_mul_f32_e32 v116, v40, v52
	v_mul_f32_e32 v117, v41, v53
	v_mul_f32_e32 v118, v42, v54
	v_mul_f32_e32 v119, v43, v55
	v_add_f32_e32 v108, v108, v116
	v_add_f32_e32 v109, v109, v117
	v_add_f32_e32 v110, v110, v118
	v_add_f32_e32 v111, v111, v119
	v_mul_f32_e32 v116, v32, v56
	v_mul_f32_e32 v117, v33, v57
	v_mul_f32_e32 v118, v34, v58
	v_mul_f32_e32 v119, v35, v59
	v_add_f32_e32 v108, v108, v116
	v_add_f32_e32 v109, v109, v117
	v_add_f32_e32 v110, v110, v118
	v_add_f32_e32 v111, v111, v119
	v_mul_f32_e32 v112, 0xbfb8aa3b, v108
	v_mul_f32_e32 v113, 0xbfb8aa3b, v109
	v_mul_f32_e32 v114, 0xbfb8aa3b, v110
	v_mul_f32_e32 v115, 0xbfb8aa3b, v111
	v_exp_f32_e32 v112, v112
	v_exp_f32_e32 v113, v113
	v_exp_f32_e32 v114, v114
	v_exp_f32_e32 v115, v115
	v_add_f32_e32 v112, 1.0, v112
	v_add_f32_e32 v113, 1.0, v113
	v_add_f32_e32 v114, 1.0, v114
	v_add_f32_e32 v115, 1.0, v115
	v_rcp_f32_e32 v112, v112
	v_rcp_f32_e32 v113, v113
	v_rcp_f32_e32 v114, v114
	v_rcp_f32_e32 v115, v115
	v_mul_f32_e32 v108, v108, v112
	v_mul_f32_e32 v109, v109, v113
	v_mul_f32_e32 v110, v110, v114
	v_mul_f32_e32 v111, v111, v115
	v_mul_f32_e32 v108, v36, v108
	v_mul_f32_e32 v109, v37, v109
	v_mul_f32_e32 v110, v38, v110
	v_mul_f32_e32 v111, v39, v111
	v_cvt_pk_bf16_f32 v116, v108, v109
	v_cvt_pk_bf16_f32 v117, v110, v111
	global_store_dwordx2 v3, v[116:117], s[22:23]
	s_cmp_lt_u32 s4, 6
	s_cbranch_scc0 .Lfix_skip3b
	s_cmp_ge_u32 s4, 3
	s_cselect_b32 s0, s22, s48
	s_cselect_b32 s1, s23, s49
	v_lshrrev_b32_e32 v2, 1, v2
	v_cndmask_b32_e64 v72, 0, v72, s[100:101]
	v_cndmask_b32_e64 v73, 0, v73, s[100:101]
	v_cndmask_b32_e64 v74, 0, v74, s[100:101]
	v_cndmask_b32_e64 v75, 0, v75, s[100:101]
	v_cndmask_b32_e64 v76, 0, v76, s[24:25]
	v_cndmask_b32_e64 v77, 0, v77, s[24:25]
	v_cndmask_b32_e64 v78, 0, v78, s[24:25]
	v_cndmask_b32_e64 v79, 0, v79, s[24:25]
	v_fma_f32 v120, v76, v80, v92
	v_fma_f32 v121, v77, v81, v93
	v_fma_f32 v122, v78, v82, v94
	v_fma_f32 v123, v79, v83, v95
	v_mul_f32_e32 v128, v72, v84
	v_mul_f32_e32 v129, v73, v85
	v_mul_f32_e32 v130, v74, v86
	v_mul_f32_e32 v131, v75, v87
	v_add_f32_e32 v120, v120, v128
	v_add_f32_e32 v121, v121, v129
	v_add_f32_e32 v122, v122, v130
	v_add_f32_e32 v123, v123, v131
	v_mul_f32_e32 v128, v64, v88
	v_mul_f32_e32 v129, v65, v89
	v_mul_f32_e32 v130, v66, v90
	v_mul_f32_e32 v131, v67, v91
	v_add_f32_e32 v120, v120, v128
	v_add_f32_e32 v121, v121, v129
	v_add_f32_e32 v122, v122, v130
	v_add_f32_e32 v123, v123, v131
	v_mul_f32_e32 v124, 0xbfb8aa3b, v120
	v_mul_f32_e32 v125, 0xbfb8aa3b, v121
	v_mul_f32_e32 v126, 0xbfb8aa3b, v122
	v_mul_f32_e32 v127, 0xbfb8aa3b, v123
	v_exp_f32_e32 v124, v124
	v_exp_f32_e32 v125, v125
	v_exp_f32_e32 v126, v126
	v_exp_f32_e32 v127, v127
	v_add_f32_e32 v124, 1.0, v124
	v_add_f32_e32 v125, 1.0, v125
	v_add_f32_e32 v126, 1.0, v126
	v_add_f32_e32 v127, 1.0, v127
	v_rcp_f32_e32 v124, v124
	v_rcp_f32_e32 v125, v125
	v_rcp_f32_e32 v126, v126
	v_rcp_f32_e32 v127, v127
	v_mul_f32_e32 v120, v120, v124
	v_mul_f32_e32 v121, v121, v125
	v_mul_f32_e32 v122, v122, v126
	v_mul_f32_e32 v123, v123, v127
	v_mul_f32_e32 v120, v68, v120
	v_mul_f32_e32 v121, v69, v121
	v_mul_f32_e32 v122, v70, v122
	v_mul_f32_e32 v123, v71, v123
	v_cvt_pk_bf16_f32 v128, v120, v121
	v_cvt_pk_bf16_f32 v129, v122, v123
	global_store_dwordx2 v2, v[128:129], s[0:1]
.Lfix_skip3b:
.LBB0_1164:
	s_waitcnt vmcnt(0)
	s_cmpk_lt_i32 s58, 0x58
	v_mov_b32_e32 v1, v0
	s_barrier
	s_cselect_b64 s[4:5], -1, 0
	s_cmpk_gt_i32 s58, 0x57
	s_nop 0
	v_readfirstlane_b32 s12, v1
	s_cbranch_scc0 .LBB0_1166
	s_lshl_b32 s1, s58, 3
	s_bfe_u32 s0, s58, 0x30003
	s_and_b32 s1, s1, 56
	s_lshr_b32 s86, s58, 6
	s_or_b32 s85, s0, s1
	s_cmpk_lt_u32 s58, 0x100
	s_mov_b32 s14, 0
	s_cselect_b64 s[2:3], -1, 0
	s_mov_b32 s67, 0
	s_andn2_b64 vcc, exec, s[2:3]
	s_cbranch_vccz .LBB0_1167
	s_branch .LBB0_1188

; __global__ void __launch_bounds__(NWAVES * 64, 2) fwd(Args args_unused) {
	.amdhsa_kernel _Z3fwd4Args
		.amdhsa_group_segment_fixed_size 0
		.amdhsa_private_segment_fixed_size 0
		.amdhsa_kernarg_size 448
		.amdhsa_user_sgpr_count 2
		.amdhsa_user_sgpr_dispatch_ptr 0
		.amdhsa_user_sgpr_queue_ptr 0
		.amdhsa_user_sgpr_kernarg_segment_ptr 1
		.amdhsa_user_sgpr_dispatch_id 0
		.amdhsa_user_sgpr_kernarg_preload_length 0
		.amdhsa_user_sgpr_kernarg_preload_offset 0
		.amdhsa_user_sgpr_private_segment_size 0
		.amdhsa_uses_dynamic_stack 0
		.amdhsa_enable_private_segment 0
		.amdhsa_system_sgpr_workgroup_id_x 1
		.amdhsa_system_sgpr_workgroup_id_y 0
		.amdhsa_system_sgpr_workgroup_id_z 0
		.amdhsa_system_sgpr_workgroup_info 0
		.amdhsa_system_vgpr_workitem_id 0
		.amdhsa_next_free_vgpr 256
		.amdhsa_next_free_sgpr 102
		.amdhsa_accum_offset 256
		.amdhsa_reserve_vcc 1
		.amdhsa_float_round_mode_32 0
		.amdhsa_float_round_mode_16_64 0
		.amdhsa_float_denorm_mode_32 3
		.amdhsa_float_denorm_mode_16_64 3
		.amdhsa_dx10_clamp 1
		.amdhsa_ieee_mode 1
		.amdhsa_fp16_overflow 0
		.amdhsa_tg_split 0
		.amdhsa_exception_fp_ieee_invalid_op 0
		.amdhsa_exception_fp_denorm_src 0
		.amdhsa_exception_fp_ieee_div_zero 0
		.amdhsa_exception_fp_ieee_overflow 0
		.amdhsa_exception_fp_ieee_underflow 0
		.amdhsa_exception_fp_ieee_inexact 0
		.amdhsa_exception_int_div_zero 0
	.end_amdhsa_kernel

; __global__ void __launch_bounds__(NWAVES * 64, 2) fwd(Args args_unused) {
amdhsa.kernels:
  - .agpr_count:     0
    .args:
      - .offset:         0
        .size:           192
        .value_kind:     by_value
      - .offset:         192
        .size:           4
        .value_kind:     hidden_block_count_x
      - .offset:         196
        .size:           4
        .value_kind:     hidden_block_count_y
      - .offset:         200
        .size:           4
        .value_kind:     hidden_block_count_z
      - .offset:         204
        .size:           2
        .value_kind:     hidden_group_size_x
      - .offset:         206
        .size:           2
        .value_kind:     hidden_group_size_y
      - .offset:         208
        .size:           2
        .value_kind:     hidden_group_size_z
      - .offset:         210
        .size:           2
        .value_kind:     hidden_remainder_x
      - .offset:         212
        .size:           2
        .value_kind:     hidden_remainder_y
      - .offset:         214
        .size:           2
        .value_kind:     hidden_remainder_z
      - .offset:         232
        .size:           8
        .value_kind:     hidden_global_offset_x
      - .offset:         240
        .size:           8
        .value_kind:     hidden_global_offset_y
      - .offset:         248
        .size:           8
        .value_kind:     hidden_global_offset_z
      - .offset:         256
        .size:           2
        .value_kind:     hidden_grid_dims
      - .offset:         312
        .size:           4
        .value_kind:     hidden_dynamic_lds_size
    .group_segment_fixed_size: 0
    .kernarg_segment_align: 8
    .kernarg_segment_size: 448
    .language:       OpenCL C
    .language_version:
      - 2
      - 0
    .max_flat_workgroup_size: 512
    .name:           _Z3fwd4Args
    .private_segment_fixed_size: 0
    .sgpr_count:     108
    .sgpr_spill_count: 27
    .symbol:         _Z3fwd4Args.kd
    .uniform_work_group_size: 1
    .uses_dynamic_stack: false
    .vgpr_count:     256
    .vgpr_spill_count: 0
    .wavefront_size: 64
